# hand-written weight conversion loop (batched loads, LDS transpose) + deferral of 8192 weight-conversion items into idle CUs of the layer-2 QKV phase
# baseline (speedup 1.0000x reference)
.LBB0_453:
	s_andn2_b64 vcc, exec, s[8:9]
	s_cbranch_vccnz .LBB0_459
	s_mov_b32 s0, s80
	s_cmpk_lt_i32 s0, 0x41
	s_cbranch_scc1 .LBB0_459
	s_mov_b64 s[0:1], s[78:79]
	v_mov_b32_e32 v2, v170
	s_mov_b32 s4, s76
	s_waitcnt vmcnt(0) lgkmcnt(0)
	s_barrier
	s_cmp_lt_i32 s4, 64
	v_readfirstlane_b32 s2, v2
	s_cbranch_scc1 .LBB0_459
	v_and_b32_e32 v2, 63, v170
	v_lshrrev_b32_e32 v3, 6, v170
	v_lshrrev_b32_e32 v82, 4, v2
	v_and_b32_e32 v83, 15, v2
	v_readfirstlane_b32 s2, v3
	v_lshlrev_b32_e32 v83, 4, v83
	v_lshrrev_b32_e32 v84, 3, v2
	v_and_b32_e32 v85, 7, v2
	s_mul_i32 s32, s2, 0x4100
	v_mul_u32_u24_e32 v86, 0x104, v82
	v_add3_u32 v86, v86, v83, s32
	v_mul_u32_u24_e32 v87, 0x820, v85
	v_lshlrev_b32_e32 v84, 2, v84
	v_add3_u32 v87, v87, v84, s32
	v_add_u32_e32 v88, 0x400, v87
	v_lshlrev_b32_e32 v82, 2, v82
	v_lshlrev_b32_e32 v85, 4, v85
	s_add_i32 s15, s76, 0xffffffc0
	s_lshl_b32 s15, s15, 3
	s_add_i32 s15, s15, s2
.Lcvb_loop:
	s_cmp_ge_u32 s15, 0x2000
	s_cbranch_scc1 .Lcvb_exit
	s_add_i32 s2, s15, 0x3000
	s_cmp_lt_u32 s15, 0x1000
	s_cbranch_scc1 .Lcvb_go
	s_add_i32 s2, s15, 0x6000
.Lcvb_go:
	s_mov_b32 s14, 0
	s_cmp_lt_u32 s2, 0x4000
	s_cbranch_scc0 .Lcvb_k1
	s_lshr_b32 s32, s2, 12
	s_and_b32 s2, s2, 0xfff
	s_movk_i32 s98, 0x80
	s_lshl_b32 s99, s32, 26
	s_mov_b32 s100, 7
	s_mov_b32 s11, 0x2000
	s_mul_i32 s101, s32, 0x2100000
	s_add_u32 s101, s101, 0x600000
	s_movk_i32 s12, 0x840
	s_mov_b32 s14, 1
	s_movk_i32 s10, 0x78
	s_lshl_b32 s13, s32, 13
	s_branch .Lcvb_dec
.Lcvb_k1:
	s_cmp_lt_u32 s2, 0x8000
	s_cbranch_scc0 .Lcvb_k2
	s_sub_u32 s2, s2, 0x4000
	s_lshr_b32 s32, s2, 12
	s_and_b32 s2, s2, 0xfff
	s_movk_i32 s98, 0x88
	s_lshl_b32 s99, s32, 26
	s_mov_b32 s100, 5
	s_mov_b32 s11, 0x800
	s_mul_i32 s101, s32, 0x2040000
	s_add_u32 s101, s101, 0x8a00000
	s_movk_i32 s12, 0x2040
	s_branch .Lcvb_dec
.Lcvb_k2:
	s_cmp_lt_u32 s2, 0x8400
	s_cbranch_scc0 .Lcvb_k3
	s_sub_u32 s2, s2, 0x8000
	s_movk_i32 s98, 0x60
	s_mov_b32 s99, 0
	s_mov_b32 s100, 5
	s_mov_b32 s11, 0x800
	s_mov_b32 s101, 0x10b00000
	s_movk_i32 s12, 0x840
	s_mov_b32 s14, 1
	s_movk_i32 s10, 0x58
	s_mov_b32 s13, 0
	s_branch .Lcvb_dec
.Lcvb_k3:
	s_cmp_lt_u32 s2, 0x8800
	s_cbranch_scc0 .Lcvb_k4
	s_sub_u32 s2, s2, 0x8400
	s_movk_i32 s98, 0x60
	s_mov_b32 s99, 0x1000000
	s_mov_b32 s100, 5
	s_mov_b32 s11, 0x800
	s_mov_b32 s101, 0x11600000
	s_movk_i32 s12, 0x840
	s_mov_b32 s14, 1
	s_movk_i32 s10, 0x58
	s_mov_b32 s13, 0x2000
	s_branch .Lcvb_dec
.Lcvb_k4:
	s_cmp_lt_u32 s2, 0x8880
	s_cbranch_scc0 .Lcvb_k5
	s_sub_u32 s2, s2, 0x8800
	s_movk_i32 s98, 0x48
	s_mov_b32 s99, 0
	s_mov_b32 s100, 2
	s_mov_b32 s11, 0x100
	s_mov_b32 s101, 0x11340000
	s_movk_i32 s12, 0x840
	s_mov_b32 s14, 1
	s_movk_i32 s10, 0x40
	s_mov_b32 s13, 0
	s_branch .Lcvb_dec
.Lcvb_k5:
	s_cmp_lt_u32 s2, 0x8900
	s_cbranch_scc0 .Lcvb_k6
	s_sub_u32 s2, s2, 0x8880
	s_movk_i32 s98, 0x50
	s_mov_b32 s99, 0
	s_mov_b32 s100, 2
	s_mov_b32 s11, 0x100
	s_mov_b32 s101, 0x11448000
	s_movk_i32 s12, 0x840
	s_mov_b32 s14, 1
	s_movk_i32 s10, 0x40
	s_mov_b32 s13, 0
	s_branch .Lcvb_dec
.Lcvb_k6:
	s_cmp_lt_u32 s2, 0x9100
	s_cbranch_scc0 .Lcvb_k7
	s_sub_u32 s2, s2, 0x8900
	s_lshr_b32 s32, s2, 10
	s_and_b32 s2, s2, 0x3ff
	s_movk_i32 s98, 0x68
	s_lshl_b32 s99, s32, 24
	s_mov_b32 s100, 5
	s_mov_b32 s11, 0x800
	s_mul_i32 s101, s32, 0x840000
	s_add_u32 s101, s101, 0x11f00000
	s_movk_i32 s12, 0x840
	s_branch .Lcvb_dec
.Lcvb_k7:
	s_sub_u32 s2, s2, 0x9100
	s_lshr_b32 s32, s2, 6
	s_and_b32 s2, s2, 63
	s_movk_i32 s98, 0x30
	s_lshl_b32 s99, s32, 20
	s_mov_b32 s100, 3
	s_mov_b32 s11, 0x200
	s_mul_i32 s101, s32, 0x90000
	s_add_u32 s101, s101, 0x100000
	s_movk_i32 s12, 0x240
	s_mov_b32 s14, 2
	s_movk_i32 s10, 0x38
	s_lshl_b32 s13, s32, 11
.Lcvb_dec:
	s_load_dwordx2 s[0:1], s[78:79], s98
	s_load_dwordx2 s[4:5], s[78:79], 0xa0
	s_cmp_eq_u32 s14, 0
	s_cbranch_scc1 .Lcvb_nsl
	s_load_dwordx2 s[6:7], s[78:79], s10
.Lcvb_nsl:
	s_lshr_b32 s32, s2, s100
	s_bfm_b32 vcc_lo, s100, 0
	s_and_b32 s2, s2, vcc_lo
	s_lshl_b32 vcc_lo, s11, 8
	s_mul_i32 vcc_lo, vcc_lo, s32
	s_add_u32 s99, s99, vcc_lo
	s_lshl_b32 vcc_lo, s2, 8
	s_add_u32 s99, s99, vcc_lo
	s_lshl_b32 vcc_lo, s12, 7
	s_mul_i32 vcc_lo, vcc_lo, s2
	s_add_u32 s101, s101, vcc_lo
	s_lshl_b32 vcc_lo, s32, 7
	s_add_u32 s101, s101, vcc_lo
	s_cmp_eq_u32 s14, 2
	s_cselect_b32 vcc_lo, s2, s32
	s_lshl_b32 vcc_lo, vcc_lo, 8
	s_add_u32 s13, s13, vcc_lo
	s_waitcnt lgkmcnt(0)
	s_add_u32 s0, s0, s99
	s_addc_u32 s1, s1, 0
	s_add_u32 s4, s4, s101
	s_addc_u32 s5, s5, 0
	s_add_u32 s6, s6, s13
	s_addc_u32 s7, s7, 0
	s_lshl_b32 s10, s11, 4
	s_lshl_b32 s13, s12, 4
	s_lshr_b32 s12, s12, 1
	v_mad_u32_u24 v89, v82, s11, v83
	v_mad_u32_u24 v0, v84, s12, v85
	global_load_dwordx4 v[2:5], v89, s[0:1]
	s_add_u32 s0, s0, s10
	s_addc_u32 s1, s1, 0
	global_load_dwordx4 v[6:9], v89, s[0:1]
	s_add_u32 s0, s0, s10
	s_addc_u32 s1, s1, 0
	global_load_dwordx4 v[10:13], v89, s[0:1]
	s_add_u32 s0, s0, s10
	s_addc_u32 s1, s1, 0
	global_load_dwordx4 v[14:17], v89, s[0:1]
	s_add_u32 s0, s0, s10
	s_addc_u32 s1, s1, 0
	global_load_dwordx4 v[18:21], v89, s[0:1]
	s_add_u32 s0, s0, s10
	s_addc_u32 s1, s1, 0
	global_load_dwordx4 v[22:25], v89, s[0:1]
	s_add_u32 s0, s0, s10
	s_addc_u32 s1, s1, 0
	global_load_dwordx4 v[26:29], v89, s[0:1]
	s_add_u32 s0, s0, s10
	s_addc_u32 s1, s1, 0
	global_load_dwordx4 v[30:33], v89, s[0:1]
	s_add_u32 s0, s0, s10
	s_addc_u32 s1, s1, 0
	global_load_dwordx4 v[34:37], v89, s[0:1]
	s_add_u32 s0, s0, s10
	s_addc_u32 s1, s1, 0
	global_load_dwordx4 v[38:41], v89, s[0:1]
	s_add_u32 s0, s0, s10
	s_addc_u32 s1, s1, 0
	global_load_dwordx4 v[42:45], v89, s[0:1]
	s_add_u32 s0, s0, s10
	s_addc_u32 s1, s1, 0
	global_load_dwordx4 v[46:49], v89, s[0:1]
	s_add_u32 s0, s0, s10
	s_addc_u32 s1, s1, 0
	global_load_dwordx4 v[50:53], v89, s[0:1]
	s_add_u32 s0, s0, s10
	s_addc_u32 s1, s1, 0
	global_load_dwordx4 v[54:57], v89, s[0:1]
	s_add_u32 s0, s0, s10
	s_addc_u32 s1, s1, 0
	global_load_dwordx4 v[58:61], v89, s[0:1]
	s_add_u32 s0, s0, s10
	s_addc_u32 s1, s1, 0
	global_load_dwordx4 v[62:65], v89, s[0:1]
	s_cmp_eq_u32 s14, 1
	s_cbranch_scc0 .Lcvb_nrs
	global_load_dword v66, v82, s[6:7] offset:0
	global_load_dword v67, v82, s[6:7] offset:16
	global_load_dword v68, v82, s[6:7] offset:32
	global_load_dword v69, v82, s[6:7] offset:48
	global_load_dword v70, v82, s[6:7] offset:64
	global_load_dword v71, v82, s[6:7] offset:80
	global_load_dword v72, v82, s[6:7] offset:96
	global_load_dword v73, v82, s[6:7] offset:112
	global_load_dword v74, v82, s[6:7] offset:128
	global_load_dword v75, v82, s[6:7] offset:144
	global_load_dword v76, v82, s[6:7] offset:160
	global_load_dword v77, v82, s[6:7] offset:176
	global_load_dword v78, v82, s[6:7] offset:192
	global_load_dword v79, v82, s[6:7] offset:208
	global_load_dword v80, v82, s[6:7] offset:224
	global_load_dword v81, v82, s[6:7] offset:240
.Lcvb_nrs:
	s_cmp_eq_u32 s14, 2
	s_cbranch_scc0 .Lcvb_ncs
	global_load_dword v66, v84, s[6:7] offset:0
	global_load_dword v67, v84, s[6:7] offset:32
	global_load_dword v68, v84, s[6:7] offset:64
	global_load_dword v69, v84, s[6:7] offset:96
	global_load_dword v70, v84, s[6:7] offset:128
	global_load_dword v71, v84, s[6:7] offset:160
	global_load_dword v72, v84, s[6:7] offset:192
	global_load_dword v73, v84, s[6:7] offset:224
.Lcvb_ncs:
	s_waitcnt vmcnt(0)
	s_cmp_eq_u32 s14, 1
	s_cbranch_scc0 .Lcvb_nrm
	v_mul_f32_e32 v2, v66, v2
	v_mul_f32_e32 v3, v66, v3
	v_mul_f32_e32 v4, v66, v4
	v_mul_f32_e32 v5, v66, v5
	v_mul_f32_e32 v6, v67, v6
	v_mul_f32_e32 v7, v67, v7
	v_mul_f32_e32 v8, v67, v8
	v_mul_f32_e32 v9, v67, v9
	v_mul_f32_e32 v10, v68, v10
	v_mul_f32_e32 v11, v68, v11
	v_mul_f32_e32 v12, v68, v12
	v_mul_f32_e32 v13, v68, v13
	v_mul_f32_e32 v14, v69, v14
	v_mul_f32_e32 v15, v69, v15
	v_mul_f32_e32 v16, v69, v16
	v_mul_f32_e32 v17, v69, v17
	v_mul_f32_e32 v18, v70, v18
	v_mul_f32_e32 v19, v70, v19
	v_mul_f32_e32 v20, v70, v20
	v_mul_f32_e32 v21, v70, v21
	v_mul_f32_e32 v22, v71, v22
	v_mul_f32_e32 v23, v71, v23
	v_mul_f32_e32 v24, v71, v24
	v_mul_f32_e32 v25, v71, v25
	v_mul_f32_e32 v26, v72, v26
	v_mul_f32_e32 v27, v72, v27
	v_mul_f32_e32 v28, v72, v28
	v_mul_f32_e32 v29, v72, v29
	v_mul_f32_e32 v30, v73, v30
	v_mul_f32_e32 v31, v73, v31
	v_mul_f32_e32 v32, v73, v32
	v_mul_f32_e32 v33, v73, v33
	v_mul_f32_e32 v34, v74, v34
	v_mul_f32_e32 v35, v74, v35
	v_mul_f32_e32 v36, v74, v36
	v_mul_f32_e32 v37, v74, v37
	v_mul_f32_e32 v38, v75, v38
	v_mul_f32_e32 v39, v75, v39
	v_mul_f32_e32 v40, v75, v40
	v_mul_f32_e32 v41, v75, v41
	v_mul_f32_e32 v42, v76, v42
	v_mul_f32_e32 v43, v76, v43
	v_mul_f32_e32 v44, v76, v44
	v_mul_f32_e32 v45, v76, v45
	v_mul_f32_e32 v46, v77, v46
	v_mul_f32_e32 v47, v77, v47
	v_mul_f32_e32 v48, v77, v48
	v_mul_f32_e32 v49, v77, v49
	v_mul_f32_e32 v50, v78, v50
	v_mul_f32_e32 v51, v78, v51
	v_mul_f32_e32 v52, v78, v52
	v_mul_f32_e32 v53, v78, v53
	v_mul_f32_e32 v54, v79, v54
	v_mul_f32_e32 v55, v79, v55
	v_mul_f32_e32 v56, v79, v56
	v_mul_f32_e32 v57, v79, v57
	v_mul_f32_e32 v58, v80, v58
	v_mul_f32_e32 v59, v80, v59
	v_mul_f32_e32 v60, v80, v60
	v_mul_f32_e32 v61, v80, v61
	v_mul_f32_e32 v62, v81, v62
	v_mul_f32_e32 v63, v81, v63
	v_mul_f32_e32 v64, v81, v64
	v_mul_f32_e32 v65, v81, v65
.Lcvb_nrm:
	ds_write_b32 v86, v2 offset:0
	ds_write_b32 v86, v3 offset:4
	ds_write_b32 v86, v4 offset:8
	ds_write_b32 v86, v5 offset:12
	ds_write_b32 v86, v6 offset:1040
	ds_write_b32 v86, v7 offset:1044
	ds_write_b32 v86, v8 offset:1048
	ds_write_b32 v86, v9 offset:1052
	ds_write_b32 v86, v10 offset:2080
	ds_write_b32 v86, v11 offset:2084
	ds_write_b32 v86, v12 offset:2088
	ds_write_b32 v86, v13 offset:2092
	ds_write_b32 v86, v14 offset:3120
	ds_write_b32 v86, v15 offset:3124
	ds_write_b32 v86, v16 offset:3128
	ds_write_b32 v86, v17 offset:3132
	ds_write_b32 v86, v18 offset:4160
	ds_write_b32 v86, v19 offset:4164
	ds_write_b32 v86, v20 offset:4168
	ds_write_b32 v86, v21 offset:4172
	ds_write_b32 v86, v22 offset:5200
	ds_write_b32 v86, v23 offset:5204
	ds_write_b32 v86, v24 offset:5208
	ds_write_b32 v86, v25 offset:5212
	ds_write_b32 v86, v26 offset:6240
	ds_write_b32 v86, v27 offset:6244
	ds_write_b32 v86, v28 offset:6248
	ds_write_b32 v86, v29 offset:6252
	ds_write_b32 v86, v30 offset:7280
	ds_write_b32 v86, v31 offset:7284
	ds_write_b32 v86, v32 offset:7288
	ds_write_b32 v86, v33 offset:7292
	ds_write_b32 v86, v34 offset:8320
	ds_write_b32 v86, v35 offset:8324
	ds_write_b32 v86, v36 offset:8328
	ds_write_b32 v86, v37 offset:8332
	ds_write_b32 v86, v38 offset:9360
	ds_write_b32 v86, v39 offset:9364
	ds_write_b32 v86, v40 offset:9368
	ds_write_b32 v86, v41 offset:9372
	ds_write_b32 v86, v42 offset:10400
	ds_write_b32 v86, v43 offset:10404
	ds_write_b32 v86, v44 offset:10408
	ds_write_b32 v86, v45 offset:10412
	ds_write_b32 v86, v46 offset:11440
	ds_write_b32 v86, v47 offset:11444
	ds_write_b32 v86, v48 offset:11448
	ds_write_b32 v86, v49 offset:11452
	ds_write_b32 v86, v50 offset:12480
	ds_write_b32 v86, v51 offset:12484
	ds_write_b32 v86, v52 offset:12488
	ds_write_b32 v86, v53 offset:12492
	ds_write_b32 v86, v54 offset:13520
	ds_write_b32 v86, v55 offset:13524
	ds_write_b32 v86, v56 offset:13528
	ds_write_b32 v86, v57 offset:13532
	ds_write_b32 v86, v58 offset:14560
	ds_write_b32 v86, v59 offset:14564
	ds_write_b32 v86, v60 offset:14568
	ds_write_b32 v86, v61 offset:14572
	ds_write_b32 v86, v62 offset:15600
	ds_write_b32 v86, v63 offset:15604
	ds_write_b32 v86, v64 offset:15608
	ds_write_b32 v86, v65 offset:15612
	s_waitcnt lgkmcnt(0)
	ds_read2_b32 v[2:3], v87 offset0:0 offset1:65
	ds_read2_b32 v[4:5], v87 offset0:130 offset1:195
	ds_read2_b32 v[6:7], v88 offset0:4 offset1:69
	ds_read2_b32 v[8:9], v88 offset0:134 offset1:199
	ds_read2_b32 v[10:11], v87 offset0:8 offset1:73
	ds_read2_b32 v[12:13], v87 offset0:138 offset1:203
	ds_read2_b32 v[14:15], v88 offset0:12 offset1:77
	ds_read2_b32 v[16:17], v88 offset0:142 offset1:207
	ds_read2_b32 v[18:19], v87 offset0:16 offset1:81
	ds_read2_b32 v[20:21], v87 offset0:146 offset1:211
	ds_read2_b32 v[22:23], v88 offset0:20 offset1:85
	ds_read2_b32 v[24:25], v88 offset0:150 offset1:215
	ds_read2_b32 v[26:27], v87 offset0:24 offset1:89
	ds_read2_b32 v[28:29], v87 offset0:154 offset1:219
	ds_read2_b32 v[30:31], v88 offset0:28 offset1:93
	ds_read2_b32 v[32:33], v88 offset0:158 offset1:223
	ds_read2_b32 v[34:35], v87 offset0:32 offset1:97
	ds_read2_b32 v[36:37], v87 offset0:162 offset1:227
	ds_read2_b32 v[38:39], v88 offset0:36 offset1:101
	ds_read2_b32 v[40:41], v88 offset0:166 offset1:231
	ds_read2_b32 v[42:43], v87 offset0:40 offset1:105
	ds_read2_b32 v[44:45], v87 offset0:170 offset1:235
	ds_read2_b32 v[46:47], v88 offset0:44 offset1:109
	ds_read2_b32 v[48:49], v88 offset0:174 offset1:239
	ds_read2_b32 v[50:51], v87 offset0:48 offset1:113
	ds_read2_b32 v[52:53], v87 offset0:178 offset1:243
	ds_read2_b32 v[54:55], v88 offset0:52 offset1:117
	ds_read2_b32 v[56:57], v88 offset0:182 offset1:247
	ds_read2_b32 v[58:59], v87 offset0:56 offset1:121
	ds_read2_b32 v[60:61], v87 offset0:186 offset1:251
	ds_read2_b32 v[62:63], v88 offset0:60 offset1:125
	ds_read2_b32 v[64:65], v88 offset0:190 offset1:255
	s_waitcnt lgkmcnt(0)
	s_cmp_eq_u32 s14, 2
	s_cbranch_scc0 .Lcvb_ncm
	v_mul_f32_e32 v2, v66, v2
	v_mul_f32_e32 v3, v66, v3
	v_mul_f32_e32 v4, v66, v4
	v_mul_f32_e32 v5, v66, v5
	v_mul_f32_e32 v6, v66, v6
	v_mul_f32_e32 v7, v66, v7
	v_mul_f32_e32 v8, v66, v8
	v_mul_f32_e32 v9, v66, v9
	v_mul_f32_e32 v10, v67, v10
	v_mul_f32_e32 v11, v67, v11
	v_mul_f32_e32 v12, v67, v12
	v_mul_f32_e32 v13, v67, v13
	v_mul_f32_e32 v14, v67, v14
	v_mul_f32_e32 v15, v67, v15
	v_mul_f32_e32 v16, v67, v16
	v_mul_f32_e32 v17, v67, v17
	v_mul_f32_e32 v18, v68, v18
	v_mul_f32_e32 v19, v68, v19
	v_mul_f32_e32 v20, v68, v20
	v_mul_f32_e32 v21, v68, v21
	v_mul_f32_e32 v22, v68, v22
	v_mul_f32_e32 v23, v68, v23
	v_mul_f32_e32 v24, v68, v24
	v_mul_f32_e32 v25, v68, v25
	v_mul_f32_e32 v26, v69, v26
	v_mul_f32_e32 v27, v69, v27
	v_mul_f32_e32 v28, v69, v28
	v_mul_f32_e32 v29, v69, v29
	v_mul_f32_e32 v30, v69, v30
	v_mul_f32_e32 v31, v69, v31
	v_mul_f32_e32 v32, v69, v32
	v_mul_f32_e32 v33, v69, v33
	v_mul_f32_e32 v34, v70, v34
	v_mul_f32_e32 v35, v70, v35
	v_mul_f32_e32 v36, v70, v36
	v_mul_f32_e32 v37, v70, v37
	v_mul_f32_e32 v38, v70, v38
	v_mul_f32_e32 v39, v70, v39
	v_mul_f32_e32 v40, v70, v40
	v_mul_f32_e32 v41, v70, v41
	v_mul_f32_e32 v42, v71, v42
	v_mul_f32_e32 v43, v71, v43
	v_mul_f32_e32 v44, v71, v44
	v_mul_f32_e32 v45, v71, v45
	v_mul_f32_e32 v46, v71, v46
	v_mul_f32_e32 v47, v71, v47
	v_mul_f32_e32 v48, v71, v48
	v_mul_f32_e32 v49, v71, v49
	v_mul_f32_e32 v50, v72, v50
	v_mul_f32_e32 v51, v72, v51
	v_mul_f32_e32 v52, v72, v52
	v_mul_f32_e32 v53, v72, v53
	v_mul_f32_e32 v54, v72, v54
	v_mul_f32_e32 v55, v72, v55
	v_mul_f32_e32 v56, v72, v56
	v_mul_f32_e32 v57, v72, v57
	v_mul_f32_e32 v58, v73, v58
	v_mul_f32_e32 v59, v73, v59
	v_mul_f32_e32 v60, v73, v60
	v_mul_f32_e32 v61, v73, v61
	v_mul_f32_e32 v62, v73, v62
	v_mul_f32_e32 v63, v73, v63
	v_mul_f32_e32 v64, v73, v64
	v_mul_f32_e32 v65, v73, v65
.Lcvb_ncm:
	v_cvt_pk_bf16_f32 v2, v2, v3
	v_cvt_pk_bf16_f32 v3, v4, v5
	v_cvt_pk_bf16_f32 v4, v6, v7
	v_cvt_pk_bf16_f32 v5, v8, v9
	global_store_dwordx4 v0, v[2:5], s[4:5]
	s_add_u32 s4, s4, s13
	s_addc_u32 s5, s5, 0
	v_cvt_pk_bf16_f32 v10, v10, v11
	v_cvt_pk_bf16_f32 v11, v12, v13
	v_cvt_pk_bf16_f32 v12, v14, v15
	v_cvt_pk_bf16_f32 v13, v16, v17
	global_store_dwordx4 v0, v[10:13], s[4:5]
	s_add_u32 s4, s4, s13
	s_addc_u32 s5, s5, 0
	v_cvt_pk_bf16_f32 v18, v18, v19
	v_cvt_pk_bf16_f32 v19, v20, v21
	v_cvt_pk_bf16_f32 v20, v22, v23
	v_cvt_pk_bf16_f32 v21, v24, v25
	global_store_dwordx4 v0, v[18:21], s[4:5]
	s_add_u32 s4, s4, s13
	s_addc_u32 s5, s5, 0
	v_cvt_pk_bf16_f32 v26, v26, v27
	v_cvt_pk_bf16_f32 v27, v28, v29
	v_cvt_pk_bf16_f32 v28, v30, v31
	v_cvt_pk_bf16_f32 v29, v32, v33
	global_store_dwordx4 v0, v[26:29], s[4:5]
	s_add_u32 s4, s4, s13
	s_addc_u32 s5, s5, 0
	v_cvt_pk_bf16_f32 v34, v34, v35
	v_cvt_pk_bf16_f32 v35, v36, v37
	v_cvt_pk_bf16_f32 v36, v38, v39
	v_cvt_pk_bf16_f32 v37, v40, v41
	global_store_dwordx4 v0, v[34:37], s[4:5]
	s_add_u32 s4, s4, s13
	s_addc_u32 s5, s5, 0
	v_cvt_pk_bf16_f32 v42, v42, v43
	v_cvt_pk_bf16_f32 v43, v44, v45
	v_cvt_pk_bf16_f32 v44, v46, v47
	v_cvt_pk_bf16_f32 v45, v48, v49
	global_store_dwordx4 v0, v[42:45], s[4:5]
	s_add_u32 s4, s4, s13
	s_addc_u32 s5, s5, 0
	v_cvt_pk_bf16_f32 v50, v50, v51
	v_cvt_pk_bf16_f32 v51, v52, v53
	v_cvt_pk_bf16_f32 v52, v54, v55
	v_cvt_pk_bf16_f32 v53, v56, v57
	global_store_dwordx4 v0, v[50:53], s[4:5]
	s_add_u32 s4, s4, s13
	s_addc_u32 s5, s5, 0
	v_cvt_pk_bf16_f32 v58, v58, v59
	v_cvt_pk_bf16_f32 v59, v60, v61
	v_cvt_pk_bf16_f32 v60, v62, v63
	v_cvt_pk_bf16_f32 v61, v64, v65
	global_store_dwordx4 v0, v[58:61], s[4:5]
.Lcvb_next:
	s_add_i32 s15, s15, 0x600
	s_branch .Lcvb_loop
.Lcvb_exit:


.LBB0_723:
	s_andn2_b64 vcc, exec, s[0:1]
	s_cbranch_vccnz .LBB0_996
	s_waitcnt vmcnt(0)
	v_mov_b32_e32 v73, v170
	s_mov_b32 s1, s76
	s_mov_b32 s2, s80
	s_load_dwordx2 s[8:9], s[48:49], 0xa0
	v_readfirstlane_b32 s0, v73
	s_ashr_i32 s0, s0, 6
	s_lshl_b32 s4, s1, 3
	s_add_i32 s16, s4, s0
	s_cmp_gt_i32 s16, 0x92ff
	s_cbranch_scc1 .LBB0_902
	v_and_b32_e32 v2, 63, v170
	v_lshrrev_b32_e32 v3, 6, v170
	v_lshrrev_b32_e32 v83, 4, v2
	v_and_b32_e32 v84, 15, v2
	v_readfirstlane_b32 s2, v3
	v_lshlrev_b32_e32 v84, 4, v84
	v_lshrrev_b32_e32 v85, 3, v2
	v_and_b32_e32 v86, 7, v2
	s_mul_i32 s32, s2, 0x4100
	v_mul_u32_u24_e32 v87, 0x104, v83
	v_add3_u32 v87, v87, v84, s32
	v_mul_u32_u24_e32 v88, 0x820, v86
	v_lshlrev_b32_e32 v85, 2, v85
	v_add3_u32 v88, v88, v85, s32
	v_add_u32_e32 v89, 0x400, v88
	v_lshlrev_b32_e32 v83, 2, v83
	v_lshlrev_b32_e32 v86, 4, v86
	s_lshl_b32 s15, s76, 3
	s_add_i32 s15, s15, s2
.Lcva_loop:
	s_cmp_ge_u32 s15, 0x9300
	s_cbranch_scc1 .Lcva_exit
	s_cmp_lt_u32 s15, 0x3000
	s_cbranch_scc1 .Lcva_go
	s_cmp_lt_u32 s15, 0x4000
	s_cbranch_scc1 .Lcva_next
	s_cmp_lt_u32 s15, 0x7000
	s_cbranch_scc1 .Lcva_go
	s_cmp_lt_u32 s15, 0x8000
	s_cbranch_scc1 .Lcva_next
.Lcva_go:
	s_mov_b32 s2, s15
	s_mov_b32 s14, 0
	s_cmp_lt_u32 s2, 0x4000
	s_cbranch_scc0 .Lcva_k1
	s_lshr_b32 s32, s2, 12
	s_and_b32 s2, s2, 0xfff
	s_movk_i32 s98, 0x80
	s_lshl_b32 s99, s32, 26
	s_mov_b32 s100, 7
	s_mov_b32 s11, 0x2000
	s_mul_i32 s101, s32, 0x2100000
	s_add_u32 s101, s101, 0x600000
	s_movk_i32 s12, 0x840
	s_mov_b32 s14, 1
	s_movk_i32 s10, 0x78
	s_lshl_b32 s13, s32, 13
	s_branch .Lcva_dec

.Lcva_nsl:
	s_lshr_b32 s32, s2, s100
	s_bfm_b32 vcc_lo, s100, 0
	s_and_b32 s2, s2, vcc_lo
	s_lshl_b32 vcc_lo, s11, 8
	s_mul_i32 vcc_lo, vcc_lo, s32
	s_add_u32 s99, s99, vcc_lo
	s_lshl_b32 vcc_lo, s2, 8
	s_add_u32 s99, s99, vcc_lo
	s_lshl_b32 vcc_lo, s12, 7
	s_mul_i32 vcc_lo, vcc_lo, s2
	s_add_u32 s101, s101, vcc_lo
	s_lshl_b32 vcc_lo, s32, 7
	s_add_u32 s101, s101, vcc_lo
	s_cmp_eq_u32 s14, 2
	s_cselect_b32 vcc_lo, s2, s32
	s_lshl_b32 vcc_lo, vcc_lo, 8
	s_add_u32 s13, s13, vcc_lo
	s_waitcnt lgkmcnt(0)
	s_add_u32 s0, s0, s99
	s_addc_u32 s1, s1, 0
	s_add_u32 s4, s4, s101
	s_addc_u32 s5, s5, 0
	s_add_u32 s6, s6, s13
	s_addc_u32 s7, s7, 0
	s_lshl_b32 s10, s11, 4
	s_lshl_b32 s13, s12, 4
	s_lshr_b32 s12, s12, 1
	v_mad_u32_u24 v90, v83, s11, v84
	v_mad_u32_u24 v91, v85, s12, v86
	global_load_dwordx4 v[2:5], v90, s[0:1]
	s_add_u32 s0, s0, s10
	s_addc_u32 s1, s1, 0
	global_load_dwordx4 v[6:9], v90, s[0:1]
	s_add_u32 s0, s0, s10
	s_addc_u32 s1, s1, 0
	global_load_dwordx4 v[10:13], v90, s[0:1]
	s_add_u32 s0, s0, s10
	s_addc_u32 s1, s1, 0
	global_load_dwordx4 v[14:17], v90, s[0:1]
	s_add_u32 s0, s0, s10
	s_addc_u32 s1, s1, 0
	global_load_dwordx4 v[18:21], v90, s[0:1]
	s_add_u32 s0, s0, s10
	s_addc_u32 s1, s1, 0
	global_load_dwordx4 v[22:25], v90, s[0:1]
	s_add_u32 s0, s0, s10
	s_addc_u32 s1, s1, 0
	global_load_dwordx4 v[26:29], v90, s[0:1]
	s_add_u32 s0, s0, s10
	s_addc_u32 s1, s1, 0
	global_load_dwordx4 v[30:33], v90, s[0:1]
	s_add_u32 s0, s0, s10
	s_addc_u32 s1, s1, 0
	global_load_dwordx4 v[34:37], v90, s[0:1]
	s_add_u32 s0, s0, s10
	s_addc_u32 s1, s1, 0
	global_load_dwordx4 v[38:41], v90, s[0:1]
	s_add_u32 s0, s0, s10
	s_addc_u32 s1, s1, 0
	global_load_dwordx4 v[42:45], v90, s[0:1]
	s_add_u32 s0, s0, s10
	s_addc_u32 s1, s1, 0
	global_load_dwordx4 v[46:49], v90, s[0:1]
	s_add_u32 s0, s0, s10
	s_addc_u32 s1, s1, 0
	global_load_dwordx4 v[50:53], v90, s[0:1]
	s_add_u32 s0, s0, s10
	s_addc_u32 s1, s1, 0
	global_load_dwordx4 v[54:57], v90, s[0:1]
	s_add_u32 s0, s0, s10
	s_addc_u32 s1, s1, 0
	global_load_dwordx4 v[58:61], v90, s[0:1]
	s_add_u32 s0, s0, s10
	s_addc_u32 s1, s1, 0
	global_load_dwordx4 v[62:65], v90, s[0:1]
	s_cmp_eq_u32 s14, 1
	s_cbranch_scc0 .Lcva_nrs
	global_load_dword v66, v83, s[6:7] offset:0
	global_load_dword v67, v83, s[6:7] offset:16
	global_load_dword v68, v83, s[6:7] offset:32
	global_load_dword v69, v83, s[6:7] offset:48
	global_load_dword v70, v83, s[6:7] offset:64
	global_load_dword v71, v83, s[6:7] offset:80
	global_load_dword v72, v83, s[6:7] offset:96
	global_load_dword v74, v83, s[6:7] offset:112
	global_load_dword v75, v83, s[6:7] offset:128
	global_load_dword v76, v83, s[6:7] offset:144
	global_load_dword v77, v83, s[6:7] offset:160
	global_load_dword v78, v83, s[6:7] offset:176
	global_load_dword v79, v83, s[6:7] offset:192
	global_load_dword v80, v83, s[6:7] offset:208
	global_load_dword v81, v83, s[6:7] offset:224
	global_load_dword v82, v83, s[6:7] offset:240
.Lcva_nrs:
	s_cmp_eq_u32 s14, 2
	s_cbranch_scc0 .Lcva_ncs
	global_load_dword v66, v85, s[6:7] offset:0
	global_load_dword v67, v85, s[6:7] offset:32
	global_load_dword v68, v85, s[6:7] offset:64
	global_load_dword v69, v85, s[6:7] offset:96
	global_load_dword v70, v85, s[6:7] offset:128
	global_load_dword v71, v85, s[6:7] offset:160
	global_load_dword v72, v85, s[6:7] offset:192
	global_load_dword v74, v85, s[6:7] offset:224
.Lcva_ncs:
	s_waitcnt vmcnt(0)
	s_cmp_eq_u32 s14, 1
	s_cbranch_scc0 .Lcva_nrm
	v_mul_f32_e32 v2, v66, v2
	v_mul_f32_e32 v3, v66, v3
	v_mul_f32_e32 v4, v66, v4
	v_mul_f32_e32 v5, v66, v5
	v_mul_f32_e32 v6, v67, v6
	v_mul_f32_e32 v7, v67, v7
	v_mul_f32_e32 v8, v67, v8
	v_mul_f32_e32 v9, v67, v9
	v_mul_f32_e32 v10, v68, v10
	v_mul_f32_e32 v11, v68, v11
	v_mul_f32_e32 v12, v68, v12
	v_mul_f32_e32 v13, v68, v13
	v_mul_f32_e32 v14, v69, v14
	v_mul_f32_e32 v15, v69, v15
	v_mul_f32_e32 v16, v69, v16
	v_mul_f32_e32 v17, v69, v17
	v_mul_f32_e32 v18, v70, v18
	v_mul_f32_e32 v19, v70, v19
	v_mul_f32_e32 v20, v70, v20
	v_mul_f32_e32 v21, v70, v21
	v_mul_f32_e32 v22, v71, v22
	v_mul_f32_e32 v23, v71, v23
	v_mul_f32_e32 v24, v71, v24
	v_mul_f32_e32 v25, v71, v25
	v_mul_f32_e32 v26, v72, v26
	v_mul_f32_e32 v27, v72, v27
	v_mul_f32_e32 v28, v72, v28
	v_mul_f32_e32 v29, v72, v29
	v_mul_f32_e32 v30, v74, v30
	v_mul_f32_e32 v31, v74, v31
	v_mul_f32_e32 v32, v74, v32
	v_mul_f32_e32 v33, v74, v33
	v_mul_f32_e32 v34, v75, v34
	v_mul_f32_e32 v35, v75, v35
	v_mul_f32_e32 v36, v75, v36
	v_mul_f32_e32 v37, v75, v37
	v_mul_f32_e32 v38, v76, v38
	v_mul_f32_e32 v39, v76, v39
	v_mul_f32_e32 v40, v76, v40
	v_mul_f32_e32 v41, v76, v41
	v_mul_f32_e32 v42, v77, v42
	v_mul_f32_e32 v43, v77, v43
	v_mul_f32_e32 v44, v77, v44
	v_mul_f32_e32 v45, v77, v45
	v_mul_f32_e32 v46, v78, v46
	v_mul_f32_e32 v47, v78, v47
	v_mul_f32_e32 v48, v78, v48
	v_mul_f32_e32 v49, v78, v49
	v_mul_f32_e32 v50, v79, v50
	v_mul_f32_e32 v51, v79, v51
	v_mul_f32_e32 v52, v79, v52
	v_mul_f32_e32 v53, v79, v53
	v_mul_f32_e32 v54, v80, v54
	v_mul_f32_e32 v55, v80, v55
	v_mul_f32_e32 v56, v80, v56
	v_mul_f32_e32 v57, v80, v57
	v_mul_f32_e32 v58, v81, v58
	v_mul_f32_e32 v59, v81, v59
	v_mul_f32_e32 v60, v81, v60
	v_mul_f32_e32 v61, v81, v61
	v_mul_f32_e32 v62, v82, v62
	v_mul_f32_e32 v63, v82, v63
	v_mul_f32_e32 v64, v82, v64
	v_mul_f32_e32 v65, v82, v65
.Lcva_nrm:
	ds_write_b32 v87, v2 offset:0
	ds_write_b32 v87, v3 offset:4
	ds_write_b32 v87, v4 offset:8
	ds_write_b32 v87, v5 offset:12
	ds_write_b32 v87, v6 offset:1040
	ds_write_b32 v87, v7 offset:1044
	ds_write_b32 v87, v8 offset:1048
	ds_write_b32 v87, v9 offset:1052
	ds_write_b32 v87, v10 offset:2080
	ds_write_b32 v87, v11 offset:2084
	ds_write_b32 v87, v12 offset:2088
	ds_write_b32 v87, v13 offset:2092
	ds_write_b32 v87, v14 offset:3120
	ds_write_b32 v87, v15 offset:3124
	ds_write_b32 v87, v16 offset:3128
	ds_write_b32 v87, v17 offset:3132
	ds_write_b32 v87, v18 offset:4160
	ds_write_b32 v87, v19 offset:4164
	ds_write_b32 v87, v20 offset:4168
	ds_write_b32 v87, v21 offset:4172
	ds_write_b32 v87, v22 offset:5200
	ds_write_b32 v87, v23 offset:5204
	ds_write_b32 v87, v24 offset:5208
	ds_write_b32 v87, v25 offset:5212
	ds_write_b32 v87, v26 offset:6240
	ds_write_b32 v87, v27 offset:6244
	ds_write_b32 v87, v28 offset:6248
	ds_write_b32 v87, v29 offset:6252
	ds_write_b32 v87, v30 offset:7280
	ds_write_b32 v87, v31 offset:7284
	ds_write_b32 v87, v32 offset:7288
	ds_write_b32 v87, v33 offset:7292
	ds_write_b32 v87, v34 offset:8320
	ds_write_b32 v87, v35 offset:8324
	ds_write_b32 v87, v36 offset:8328
	ds_write_b32 v87, v37 offset:8332
	ds_write_b32 v87, v38 offset:9360
	ds_write_b32 v87, v39 offset:9364
	ds_write_b32 v87, v40 offset:9368
	ds_write_b32 v87, v41 offset:9372
	ds_write_b32 v87, v42 offset:10400
	ds_write_b32 v87, v43 offset:10404
	ds_write_b32 v87, v44 offset:10408
	ds_write_b32 v87, v45 offset:10412
	ds_write_b32 v87, v46 offset:11440
	ds_write_b32 v87, v47 offset:11444
	ds_write_b32 v87, v48 offset:11448
	ds_write_b32 v87, v49 offset:11452
	ds_write_b32 v87, v50 offset:12480
	ds_write_b32 v87, v51 offset:12484
	ds_write_b32 v87, v52 offset:12488
	ds_write_b32 v87, v53 offset:12492
	ds_write_b32 v87, v54 offset:13520
	ds_write_b32 v87, v55 offset:13524
	ds_write_b32 v87, v56 offset:13528
	ds_write_b32 v87, v57 offset:13532
	ds_write_b32 v87, v58 offset:14560
	ds_write_b32 v87, v59 offset:14564
	ds_write_b32 v87, v60 offset:14568
	ds_write_b32 v87, v61 offset:14572
	ds_write_b32 v87, v62 offset:15600
	ds_write_b32 v87, v63 offset:15604
	ds_write_b32 v87, v64 offset:15608
	ds_write_b32 v87, v65 offset:15612
	s_waitcnt lgkmcnt(0)
	ds_read2_b32 v[2:3], v88 offset0:0 offset1:65
	ds_read2_b32 v[4:5], v88 offset0:130 offset1:195
	ds_read2_b32 v[6:7], v89 offset0:4 offset1:69
	ds_read2_b32 v[8:9], v89 offset0:134 offset1:199
	ds_read2_b32 v[10:11], v88 offset0:8 offset1:73
	ds_read2_b32 v[12:13], v88 offset0:138 offset1:203
	ds_read2_b32 v[14:15], v89 offset0:12 offset1:77
	ds_read2_b32 v[16:17], v89 offset0:142 offset1:207
	ds_read2_b32 v[18:19], v88 offset0:16 offset1:81
	ds_read2_b32 v[20:21], v88 offset0:146 offset1:211
	ds_read2_b32 v[22:23], v89 offset0:20 offset1:85
	ds_read2_b32 v[24:25], v89 offset0:150 offset1:215
	ds_read2_b32 v[26:27], v88 offset0:24 offset1:89
	ds_read2_b32 v[28:29], v88 offset0:154 offset1:219
	ds_read2_b32 v[30:31], v89 offset0:28 offset1:93
	ds_read2_b32 v[32:33], v89 offset0:158 offset1:223
	ds_read2_b32 v[34:35], v88 offset0:32 offset1:97
	ds_read2_b32 v[36:37], v88 offset0:162 offset1:227
	ds_read2_b32 v[38:39], v89 offset0:36 offset1:101
	ds_read2_b32 v[40:41], v89 offset0:166 offset1:231
	ds_read2_b32 v[42:43], v88 offset0:40 offset1:105
	ds_read2_b32 v[44:45], v88 offset0:170 offset1:235
	ds_read2_b32 v[46:47], v89 offset0:44 offset1:109
	ds_read2_b32 v[48:49], v89 offset0:174 offset1:239
	ds_read2_b32 v[50:51], v88 offset0:48 offset1:113
	ds_read2_b32 v[52:53], v88 offset0:178 offset1:243
	ds_read2_b32 v[54:55], v89 offset0:52 offset1:117
	ds_read2_b32 v[56:57], v89 offset0:182 offset1:247
	ds_read2_b32 v[58:59], v88 offset0:56 offset1:121
	ds_read2_b32 v[60:61], v88 offset0:186 offset1:251
	ds_read2_b32 v[62:63], v89 offset0:60 offset1:125
	ds_read2_b32 v[64:65], v89 offset0:190 offset1:255
	s_waitcnt lgkmcnt(0)
	s_cmp_eq_u32 s14, 2
	s_cbranch_scc0 .Lcva_ncm
	v_mul_f32_e32 v2, v66, v2
	v_mul_f32_e32 v3, v66, v3
	v_mul_f32_e32 v4, v66, v4
	v_mul_f32_e32 v5, v66, v5
	v_mul_f32_e32 v6, v66, v6
	v_mul_f32_e32 v7, v66, v7
	v_mul_f32_e32 v8, v66, v8
	v_mul_f32_e32 v9, v66, v9
	v_mul_f32_e32 v10, v67, v10
	v_mul_f32_e32 v11, v67, v11
	v_mul_f32_e32 v12, v67, v12
	v_mul_f32_e32 v13, v67, v13
	v_mul_f32_e32 v14, v67, v14
	v_mul_f32_e32 v15, v67, v15
	v_mul_f32_e32 v16, v67, v16
	v_mul_f32_e32 v17, v67, v17
	v_mul_f32_e32 v18, v68, v18
	v_mul_f32_e32 v19, v68, v19
	v_mul_f32_e32 v20, v68, v20
	v_mul_f32_e32 v21, v68, v21
	v_mul_f32_e32 v22, v68, v22
	v_mul_f32_e32 v23, v68, v23
	v_mul_f32_e32 v24, v68, v24
	v_mul_f32_e32 v25, v68, v25
	v_mul_f32_e32 v26, v69, v26
	v_mul_f32_e32 v27, v69, v27
	v_mul_f32_e32 v28, v69, v28
	v_mul_f32_e32 v29, v69, v29
	v_mul_f32_e32 v30, v69, v30
	v_mul_f32_e32 v31, v69, v31
	v_mul_f32_e32 v32, v69, v32
	v_mul_f32_e32 v33, v69, v33
	v_mul_f32_e32 v34, v70, v34
	v_mul_f32_e32 v35, v70, v35
	v_mul_f32_e32 v36, v70, v36
	v_mul_f32_e32 v37, v70, v37
	v_mul_f32_e32 v38, v70, v38
	v_mul_f32_e32 v39, v70, v39
	v_mul_f32_e32 v40, v70, v40
	v_mul_f32_e32 v41, v70, v41
	v_mul_f32_e32 v42, v71, v42
	v_mul_f32_e32 v43, v71, v43
	v_mul_f32_e32 v44, v71, v44
	v_mul_f32_e32 v45, v71, v45
	v_mul_f32_e32 v46, v71, v46
	v_mul_f32_e32 v47, v71, v47
	v_mul_f32_e32 v48, v71, v48
	v_mul_f32_e32 v49, v71, v49
	v_mul_f32_e32 v50, v72, v50
	v_mul_f32_e32 v51, v72, v51
	v_mul_f32_e32 v52, v72, v52
	v_mul_f32_e32 v53, v72, v53
	v_mul_f32_e32 v54, v72, v54
	v_mul_f32_e32 v55, v72, v55
	v_mul_f32_e32 v56, v72, v56
	v_mul_f32_e32 v57, v72, v57
	v_mul_f32_e32 v58, v74, v58
	v_mul_f32_e32 v59, v74, v59
	v_mul_f32_e32 v60, v74, v60
	v_mul_f32_e32 v61, v74, v61
	v_mul_f32_e32 v62, v74, v62
	v_mul_f32_e32 v63, v74, v63
	v_mul_f32_e32 v64, v74, v64
	v_mul_f32_e32 v65, v74, v65
.Lcva_ncm:
	v_cvt_pk_bf16_f32 v2, v2, v3
	v_cvt_pk_bf16_f32 v3, v4, v5
	v_cvt_pk_bf16_f32 v4, v6, v7
	v_cvt_pk_bf16_f32 v5, v8, v9
	global_store_dwordx4 v91, v[2:5], s[4:5]
	s_add_u32 s4, s4, s13
	s_addc_u32 s5, s5, 0
	v_cvt_pk_bf16_f32 v10, v10, v11
	v_cvt_pk_bf16_f32 v11, v12, v13
	v_cvt_pk_bf16_f32 v12, v14, v15
	v_cvt_pk_bf16_f32 v13, v16, v17
	global_store_dwordx4 v91, v[10:13], s[4:5]
	s_add_u32 s4, s4, s13
	s_addc_u32 s5, s5, 0
	v_cvt_pk_bf16_f32 v18, v18, v19
	v_cvt_pk_bf16_f32 v19, v20, v21
	v_cvt_pk_bf16_f32 v20, v22, v23
	v_cvt_pk_bf16_f32 v21, v24, v25
	global_store_dwordx4 v91, v[18:21], s[4:5]
	s_add_u32 s4, s4, s13
	s_addc_u32 s5, s5, 0
	v_cvt_pk_bf16_f32 v26, v26, v27
	v_cvt_pk_bf16_f32 v27, v28, v29
	v_cvt_pk_bf16_f32 v28, v30, v31
	v_cvt_pk_bf16_f32 v29, v32, v33
	global_store_dwordx4 v91, v[26:29], s[4:5]
	s_add_u32 s4, s4, s13
	s_addc_u32 s5, s5, 0
	v_cvt_pk_bf16_f32 v34, v34, v35
	v_cvt_pk_bf16_f32 v35, v36, v37
	v_cvt_pk_bf16_f32 v36, v38, v39
	v_cvt_pk_bf16_f32 v37, v40, v41
	global_store_dwordx4 v91, v[34:37], s[4:5]
	s_add_u32 s4, s4, s13
	s_addc_u32 s5, s5, 0
	v_cvt_pk_bf16_f32 v42, v42, v43
	v_cvt_pk_bf16_f32 v43, v44, v45
	v_cvt_pk_bf16_f32 v44, v46, v47
	v_cvt_pk_bf16_f32 v45, v48, v49
	global_store_dwordx4 v91, v[42:45], s[4:5]
	s_add_u32 s4, s4, s13
	s_addc_u32 s5, s5, 0
	v_cvt_pk_bf16_f32 v50, v50, v51
	v_cvt_pk_bf16_f32 v51, v52, v53
	v_cvt_pk_bf16_f32 v52, v54, v55
	v_cvt_pk_bf16_f32 v53, v56, v57
	global_store_dwordx4 v91, v[50:53], s[4:5]
	s_add_u32 s4, s4, s13
	s_addc_u32 s5, s5, 0
	v_cvt_pk_bf16_f32 v58, v58, v59
	v_cvt_pk_bf16_f32 v59, v60, v61
	v_cvt_pk_bf16_f32 v60, v62, v63
	v_cvt_pk_bf16_f32 v61, v64, v65
	global_store_dwordx4 v91, v[58:61], s[4:5]
.Lcva_next:
	s_add_i32 s15, s15, 0x800
	s_branch .Lcva_loop

	.amdhsa_kernel _Z8yoco_fwd4Args
		.amdhsa_group_segment_fixed_size 0
		.amdhsa_private_segment_fixed_size 0
		.amdhsa_kernarg_size 432
		.amdhsa_user_sgpr_count 2
		.amdhsa_user_sgpr_dispatch_ptr 0
		.amdhsa_user_sgpr_queue_ptr 0
		.amdhsa_user_sgpr_kernarg_segment_ptr 1
		.amdhsa_user_sgpr_dispatch_id 0
		.amdhsa_user_sgpr_kernarg_preload_length 0
		.amdhsa_user_sgpr_kernarg_preload_offset 0
		.amdhsa_user_sgpr_private_segment_size 0
		.amdhsa_uses_dynamic_stack 0
		.amdhsa_enable_private_segment 0
		.amdhsa_system_sgpr_workgroup_id_x 1
		.amdhsa_system_sgpr_workgroup_id_y 0
		.amdhsa_system_sgpr_workgroup_id_z 0
		.amdhsa_system_sgpr_workgroup_info 0
		.amdhsa_system_vgpr_workitem_id 2
		.amdhsa_next_free_vgpr 256
		.amdhsa_next_free_sgpr 102
		.amdhsa_accum_offset 256
		.amdhsa_reserve_vcc 1
		.amdhsa_float_round_mode_32 0
		.amdhsa_float_round_mode_16_64 0
		.amdhsa_float_denorm_mode_32 3
		.amdhsa_float_denorm_mode_16_64 3
		.amdhsa_dx10_clamp 1
		.amdhsa_ieee_mode 1
		.amdhsa_fp16_overflow 0
		.amdhsa_tg_split 0
		.amdhsa_exception_fp_ieee_invalid_op 0
		.amdhsa_exception_fp_denorm_src 0
		.amdhsa_exception_fp_ieee_div_zero 0
		.amdhsa_exception_fp_ieee_overflow 0
		.amdhsa_exception_fp_ieee_underflow 0
		.amdhsa_exception_fp_ieee_inexact 0
		.amdhsa_exception_int_div_zero 0
	.end_amdhsa_kernel

amdhsa.kernels:
  - .agpr_count:     0
    .args:
      - .offset:         0
        .size:           176
        .value_kind:     by_value
      - .offset:         176
        .size:           4
        .value_kind:     hidden_block_count_x
      - .offset:         180
        .size:           4
        .value_kind:     hidden_block_count_y
      - .offset:         184
        .size:           4
        .value_kind:     hidden_block_count_z
      - .offset:         188
        .size:           2
        .value_kind:     hidden_group_size_x
      - .offset:         190
        .size:           2
        .value_kind:     hidden_group_size_y
      - .offset:         192
        .size:           2
        .value_kind:     hidden_group_size_z
      - .offset:         194
        .size:           2
        .value_kind:     hidden_remainder_x
      - .offset:         196
        .size:           2
        .value_kind:     hidden_remainder_y
      - .offset:         198
        .size:           2
        .value_kind:     hidden_remainder_z
      - .offset:         216
        .size:           8
        .value_kind:     hidden_global_offset_x
      - .offset:         224
        .size:           8
        .value_kind:     hidden_global_offset_y
      - .offset:         232
        .size:           8
        .value_kind:     hidden_global_offset_z
      - .offset:         240
        .size:           2
        .value_kind:     hidden_grid_dims
      - .offset:         264
        .size:           8
        .value_kind:     hidden_multigrid_sync_arg
      - .offset:         296
        .size:           4
        .value_kind:     hidden_dynamic_lds_size
    .group_segment_fixed_size: 0
    .kernarg_segment_align: 8
    .kernarg_segment_size: 432
    .language:       OpenCL C
    .language_version:
      - 2
      - 0
    .max_flat_workgroup_size: 512
    .name:           _Z8yoco_fwd4Args
    .private_segment_fixed_size: 0
    .sgpr_count:     108
    .sgpr_spill_count: 154
    .symbol:         _Z8yoco_fwd4Args.kd
    .uniform_work_group_size: 1
    .uses_dynamic_stack: false
    .vgpr_count:     256
    .vgpr_spill_count: 0
    .wavefront_size: 64
